# attention: finishSM exps/cvts re-ordered for equal VALU cost per QK MFMA gap; ones-refill movs into the empty PV gap
# baseline (speedup 1.0000x reference)
; #define LAS __attribute__((address_space(3)))
; template <bool FIRST>
; __device__ __forceinline__ void partialSM(f32x16& p0, f32x16& p1, f32x16& negm, float& dl, float& alpha) {
;     float pmax = p0[0];
; #pragma unroll
;     for (int r = 1; r < 16; ++r) pmax = fmaxf(pmax, p0[r]);
; #pragma unroll
;     for (int r = 0; r < 16; ++r) pmax = fmaxf(pmax, p1[r]);
;     { auto rr = __builtin_amdgcn_permlane32_swap(__float_as_uint(pmax), __float_as_uint(pmax), false, false);
;       pmax = fmaxf(__uint_as_float(rr[0]), __uint_as_float(rr[1])); }
;     if (FIRST) {
;         dl = 0.f; alpha = 1.f; const float d0_ = pmax - SH;
; #pragma unroll
;         for (int r = 0; r < 16; ++r) { p0[r] -= d0_; p1[r] -= d0_; negm[r] -= d0_; }
;     } else {
;         const bool keep = __all(pmax <= SH + THRL);
;         dl = keep ? 0.f : fmaxf(pmax - SH, 0.f); alpha = __builtin_amdgcn_exp2f(-dl);
;     }
; #pragma unroll
;     for (int r = 0; r < 16; ++r) p0[r] = __builtin_amdgcn_exp2f(p0[r]);
; }
; __device__ __forceinline__ void finishSM(f32x16& p0, f32x16& p1, v8i& pa) {
; #pragma unroll
;     for (int r = 0; r < 16; ++r) p1[r] = __builtin_amdgcn_exp2f(p1[r]);
; #pragma unroll
;     for (int w = 0; w < 4; ++w) { pa[w] = (int)pk4_fp8(p0[4 * w], p0[4 * w + 1], p0[4 * w + 2], p0[4 * w + 3]); pa[4 + w] = (int)pk4_fp8(p1[4 * w], p1[4 * w + 1], p1[4 * w + 2], p1[4 * w + 3]); }
; }
; __device__ __forceinline__ v8i ld32(const LAS char* a0, const LAS char* a1) { const v4i x = *(const LAS v4i*)a0, y = *(const LAS v4i*)a1; return (v8i){x[0], x[1], x[2], x[3], y[0], y[1], y[2], y[3]}; }
; __device__ __forceinline__ void qkt(f32x16& p0, f32x16& p1, const LAS char* Ks, int ka0, int ka1, const v8i* qf, const f32x16& negm) {
; #pragma unroll
;     for (int st = 0; st < 3; ++st) {
;         const v8i k0 = ld32(Ks + ka0 + 64 * st, Ks + ka1 + 64 * st), k1 = ld32(Ks + ka0 + 64 * st + 32 * 192, Ks + ka1 + 64 * st + 32 * 192);
;         if (st == 0) { p0 = MFMA8QK(k0, qf[st], negm); p1 = MFMA8QK(k1, qf[st], negm); }
;         else { p0 = MFMA8QK(k0, qf[st], p0); p1 = MFMA8QK(k1, qf[st], p1); } }
; }
; __device__ __forceinline__ void pv_d0(f32x16* o, const LAS char* Vs, int va0, int va1, v8i pa) {
; #pragma unroll
;     for (int d0 = 0; d0 < 4; ++d0) { const v8i vf = ld32(Vs + va0 + 2048 * d0, Vs + va1 + 2048 * d0); o[d0] = MFMA8(pa, vf, o[d0]); }
.LBB0_589:
	s_bitcmp1_b32 s15, 0
	s_cselect_b32 s0, 0x6000, 0
	s_add_i32 s0, s0, 0
	v_add_u32_e32 v0, s0, v244
	v_add_u32_e32 v210, s0, v245
	v_add_u32_e32 v211, 0xf000, v0
	v_add_u32_e32 v212, 0xf000, v210
	ds_read_b128 v[2:5], v0 offset:61504
	ds_read_b128 v[6:9], v210 offset:61504
	v_exp_f32_e32 v14, v116
	v_exp_f32_e32 v15, v117
	v_exp_f32_e32 v12, v114
	v_exp_f32_e32 v13, v115
	s_waitcnt lgkmcnt(4)
	v_mfma_scale_f32_32x32x64_f8f6f4 v[144:159], v[202:209], v[184:191], v[96:111], v234, v233 op_sel_hi:[0,0,0]
	ds_read_b128 v[202:205], v211 offset:6208
	ds_read_b128 v[206:209], v212 offset:6208
	v_exp_f32_e32 v114, v118
	v_exp_f32_e32 v115, v119
	v_exp_f32_e32 v119, v120
	v_cvt_pk_fp8_f32 v117, v14, v15
	v_exp_f32_e32 v120, v121
	s_waitcnt lgkmcnt(4)
	v_mfma_scale_f32_32x32x64_f8f6f4 v[128:143], v[194:201], v[184:191], v[96:111], v234, v233 op_sel_hi:[0,0,0]
	ds_read_b128 v[194:197], v0 offset:61568
	ds_read_b128 v[198:201], v210 offset:61568
	v_exp_f32_e32 v10, v112
	v_exp_f32_e32 v11, v113
	v_exp_f32_e32 v121, v122
	v_cvt_pk_fp8_f32 v117, v114, v115 op_sel:[0,0,1]
	v_cvt_pk_fp8_f32 v118, v119, v120
	s_waitcnt lgkmcnt(4)
	v_mfma_scale_f32_32x32x64_f8f6f4 v[144:159], v[2:9], v[176:183], v[144:159], v234, v233 op_sel_hi:[0,0,0]
	ds_read_b128 v[2:5], v211 offset:6272
	ds_read_b128 v[6:9], v212 offset:6272
	v_exp_f32_e32 v122, v123
	v_exp_f32_e32 v123, v124
	v_exp_f32_e32 v124, v125
	v_cvt_pk_fp8_f32 v116, v10, v11
	v_cvt_pk_fp8_f32 v112, v228, v229
	s_waitcnt lgkmcnt(4)
	v_mfma_scale_f32_32x32x64_f8f6f4 v[128:143], v[202:209], v[176:183], v[128:143], v234, v233 op_sel_hi:[0,0,0]
	v_exp_f32_e32 v125, v126
	v_exp_f32_e32 v126, v127
	v_cvt_pk_fp8_f32 v113, v226, v227
	v_cvt_pk_fp8_f32 v114, v222, v223
	v_cvt_pk_fp8_f32 v115, v166, v167
	v_cvt_pk_fp8_f32 v119, v123, v124
	s_waitcnt lgkmcnt(2)
	v_mfma_scale_f32_32x32x64_f8f6f4 v[144:159], v[194:201], v[168:175], v[144:159], v234, v233 op_sel_hi:[0,0,0]
	v_cvt_pk_fp8_f32 v112, v220, v221 op_sel:[0,0,1]
	v_cvt_pk_fp8_f32 v116, v12, v13 op_sel:[0,0,1]
	v_cvt_pk_fp8_f32 v113, v224, v225 op_sel:[0,0,1]
	v_cvt_pk_fp8_f32 v114, v162, v163 op_sel:[0,0,1]
	v_cvt_pk_fp8_f32 v118, v121, v122 op_sel:[0,0,1]
	v_cvt_pk_fp8_f32 v115, v164, v165 op_sel:[0,0,1]
	v_cvt_pk_fp8_f32 v119, v125, v126 op_sel:[0,0,1]
	v_mov_b32_e32 v166, v160
	v_mov_b32_e32 v167, v160
	s_waitcnt lgkmcnt(0)
	v_mfma_scale_f32_32x32x64_f8f6f4 v[128:143], v[2:9], v[168:175], v[128:143], v234, v233 op_sel_hi:[0,0,0]
	v_mov_b32_e32 v161, v160
	v_mov_b32_e32 v162, v160
	v_mov_b32_e32 v163, v160
	v_mov_b32_e32 v164, v160
	v_mov_b32_e32 v165, v160
	s_add_i32 s66, s21, -2
	s_ashr_i32 s38, s66, 1
	s_mul_hi_i32 s0, s38, 0x55555556
	s_lshr_b32 s1, s0, 31
	s_add_i32 s0, s0, s1
	s_mul_i32 s0, s0, 3
	s_sub_i32 s0, s38, s0
	s_lshl_b32 s0, s0, 14
	s_add_i32 s0, s0, 0
	v_add_u32_e32 v0, s0, v241
	v_add_u32_e32 v11, s0, v240
	ds_read_b128 v[208:211], v0
	ds_read_b128 v[212:215], v11
	ds_read_b128 v[200:203], v0 offset:2048
	ds_read_b128 v[204:207], v11 offset:2048
	ds_read_b128 v[192:195], v0 offset:4096
	ds_read_b128 v[196:199], v11 offset:4096
	ds_read_b128 v[2:5], v0 offset:6144
	ds_read_b128 v[6:9], v11 offset:6144
	v_mov_b32_e32 v125, 0x19000
	v_lshl_add_u32 v126, v216, 4, v125
	v_lshl_add_u32 v127, v216, 2, v125
	ds_read_b128 v[120:123], v126
	ds_read_b32 v124, v127 offset:8192
	v_max_f32_e32 v0, v144, v145
	v_max3_f32 v0, v0, v146, v147
	v_max3_f32 v0, v0, v148, v149
	v_max3_f32 v0, v0, v150, v151
	v_max3_f32 v0, v0, v152, v153
	v_max3_f32 v0, v0, v154, v155
	v_max3_f32 v0, v0, v156, v157
	v_max3_f32 v0, v0, v158, v159
	s_waitcnt lgkmcnt(8)
	v_mfma_scale_f32_32x32x64_f8f6f4 v[64:79], v[112:119], v[208:215], v[64:79], v234, v234 op_sel_hi:[0,0,0]
	v_exp_f32_e32 v14, v144
	v_exp_f32_e32 v15, v145
	v_exp_f32_e32 v10, v148
	v_exp_f32_e32 v11, v149
	v_max3_f32 v0, v0, v128, v129
	v_max3_f32 v0, v0, v130, v131
	v_max3_f32 v0, v0, v132, v133
	v_max3_f32 v0, v0, v134, v135
	s_waitcnt lgkmcnt(6)
	v_mfma_scale_f32_32x32x64_f8f6f4 v[48:63], v[112:119], v[200:207], v[48:63], v234, v234 op_sel_hi:[0,0,0]
	v_exp_f32_e32 v12, v150
	v_exp_f32_e32 v13, v151
	v_max3_f32 v0, v0, v136, v137
	v_max3_f32 v0, v0, v138, v139
	v_max3_f32 v0, v0, v140, v141
	v_max3_f32 v0, v0, v142, v143
	s_waitcnt lgkmcnt(4)
	v_mfma_scale_f32_32x32x64_f8f6f4 v[32:47], v[112:119], v[192:199], v[32:47], v234, v234 op_sel_hi:[0,0,0]
	v_exp_f32_e32 v192, v146
	v_exp_f32_e32 v193, v147
	v_mov_b32_e32 v125, v0
	s_nop 1
	v_permlane32_swap_b32_e32 v0, v125
	s_waitcnt lgkmcnt(2)
	v_mfma_scale_f32_32x32x64_f8f6f4 v[16:31], v[112:119], v[2:9], v[16:31], v234, v234 op_sel_hi:[0,0,0]
	v_exp_f32_e32 v6, v152
	v_exp_f32_e32 v7, v153
	v_exp_f32_e32 v8, v154
	v_exp_f32_e32 v9, v155
	v_mfma_scale_f32_32x32x64_f8f6f4 v[80:95], v[112:119], v[160:167], v[80:95], v234, v234 op_sel_hi:[0,0,0]
	v_exp_f32_e32 v2, v156
	v_exp_f32_e32 v3, v157
	v_exp_f32_e32 v4, v158
	v_exp_f32_e32 v5, v159
	s_waitcnt vmcnt(0) lgkmcnt(0)
	s_barrier
	v_max_f32_e32 v0, v0, v125
	s_add_i32 s42, s38, 2
	v_cmp_ge_f32_e64 s[0:1], s67, v0
	s_cmp_ge_i32 s42, s14
	s_cbranch_scc1 .Lattn_noissue
	s_bitcmp1_b32 s21, 1
	s_cselect_b32 s44, 0x6000, 0
	v_add_u32_e32 v126, s44, v244
	v_add_u32_e32 v127, s44, v245
	ds_read_b128 v[208:211], v126 offset:49152
	ds_read_b128 v[212:215], v127 offset:49152
	s_ashr_i32 s43, s42, 31
	s_mul_i32 s38, s42, 0x18000
	s_mul_hi_i32 s39, s42, 0x18000
	s_add_u32 s38, s24, s38
	s_addc_u32 s39, s25, s39
	s_lshl_b64 s[40:41], s[42:43], 14
	s_add_u32 s40, s52, s40
	s_addc_u32 s41, s53, s41
	s_mul_hi_i32 s43, s42, 0x55555556
	s_lshr_b32 s67, s43, 31
	s_add_i32 s43, s43, s67
	s_mul_i32 s43, s43, 3
	s_sub_i32 s42, s42, s43
	s_lshl_b32 s67, s42, 14
	s_bitcmp1_b32 s66, 1
	s_mov_b32 s42, 0xa000
	s_cselect_b32 s66, 0x10000, s42
	s_and_b64 vcc, exec, s[6:7]
	s_cbranch_vccnz .Lattn_iss_hi
	s_add_i32 m0, s67, s28
	s_nop 0
	global_load_lds_dwordx4 v120, s[40:41]
	s_add_i32 m0, s2, s66
	s_nop 0
	global_load_lds_dwordx4 v121, s[38:39]
	s_add_i32 m0, s27, s66
	s_nop 0
	global_load_lds_dwordx4 v122, s[38:39]
	s_add_i32 m0, s67, s31
	s_nop 0
	global_load_lds_dwordx4 v123, s[40:41]
	s_add_i32 m0, s33, s66
	s_nop 0
	global_load_lds_dwordx4 v124, s[38:39]
	s_branch .Lattn_iss_done

; #define LAS __attribute__((address_space(3)))
; template <bool FIRST>
; __device__ __forceinline__ void partialSM(f32x16& p0, f32x16& p1, f32x16& negm, float& dl, float& alpha) {
;     float pmax = p0[0];
; #pragma unroll
;     for (int r = 1; r < 16; ++r) pmax = fmaxf(pmax, p0[r]);
; #pragma unroll
;     for (int r = 0; r < 16; ++r) pmax = fmaxf(pmax, p1[r]);
;     { auto rr = __builtin_amdgcn_permlane32_swap(__float_as_uint(pmax), __float_as_uint(pmax), false, false);
;       pmax = fmaxf(__uint_as_float(rr[0]), __uint_as_float(rr[1])); }
;     if (FIRST) {
;         dl = 0.f; alpha = 1.f; const float d0_ = pmax - SH;
; #pragma unroll
;         for (int r = 0; r < 16; ++r) { p0[r] -= d0_; p1[r] -= d0_; negm[r] -= d0_; }
;     } else {
;         const bool keep = __all(pmax <= SH + THRL);
;         dl = keep ? 0.f : fmaxf(pmax - SH, 0.f); alpha = __builtin_amdgcn_exp2f(-dl);
;     }
; #pragma unroll
;     for (int r = 0; r < 16; ++r) p0[r] = __builtin_amdgcn_exp2f(p0[r]);
; }
; __device__ __forceinline__ void finishSM(f32x16& p0, f32x16& p1, v8i& pa) {
; #pragma unroll
;     for (int r = 0; r < 16; ++r) p1[r] = __builtin_amdgcn_exp2f(p1[r]);
; #pragma unroll
;     for (int w = 0; w < 4; ++w) { pa[w] = (int)pk4_fp8(p0[4 * w], p0[4 * w + 1], p0[4 * w + 2], p0[4 * w + 3]); pa[4 + w] = (int)pk4_fp8(p1[4 * w], p1[4 * w + 1], p1[4 * w + 2], p1[4 * w + 3]); }
; }
; __device__ __forceinline__ v8i ld32(const LAS char* a0, const LAS char* a1) { const v4i x = *(const LAS v4i*)a0, y = *(const LAS v4i*)a1; return (v8i){x[0], x[1], x[2], x[3], y[0], y[1], y[2], y[3]}; }
; __device__ __forceinline__ void qkt(f32x16& p0, f32x16& p1, const LAS char* Ks, int ka0, int ka1, const v8i* qf, const f32x16& negm) {
; #pragma unroll
;     for (int st = 0; st < 3; ++st) {
;         const v8i k0 = ld32(Ks + ka0 + 64 * st, Ks + ka1 + 64 * st), k1 = ld32(Ks + ka0 + 64 * st + 32 * 192, Ks + ka1 + 64 * st + 32 * 192);
;         if (st == 0) { p0 = MFMA8QK(k0, qf[st], negm); p1 = MFMA8QK(k1, qf[st], negm); }
;         else { p0 = MFMA8QK(k0, qf[st], p0); p1 = MFMA8QK(k1, qf[st], p1); } }
; }
; __device__ __forceinline__ void pv_d0(f32x16* o, const LAS char* Vs, int va0, int va1, v8i pa) {
; #pragma unroll
;     for (int d0 = 0; d0 < 4; ++d0) { const v8i vf = ld32(Vs + va0 + 2048 * d0, Vs + va1 + 2048 * d0); o[d0] = MFMA8(pa, vf, o[d0]); }
.LBB0_615:
	s_mul_hi_u32 s0, s15, 0xaaaaaaab
	s_lshr_b32 s0, s0, 1
	s_mul_i32 s0, s0, 0xffff4000
	s_bfe_i32 s1, s21, 0x10001
	s_and_b32 s1, s1, 0x6000
	s_add_i32 s1, s1, 0
	v_add_u32_e32 v0, s1, v244
	v_add_u32_e32 v161, s1, v245
	ds_read_b128 v[194:197], v0 offset:55360
	ds_read_b128 v[198:201], v161 offset:55360
	v_exp_f32_e32 v129, v129
	v_exp_f32_e32 v162, v133
	s_waitcnt lgkmcnt(4)
	v_mfma_scale_f32_32x32x64_f8f6f4 v[144:159], v[208:215], v[184:191], v[96:111], v234, v233 op_sel_hi:[0,0,0]
	ds_read_b128 v[202:205], v0 offset:49216
	ds_read_b128 v[206:209], v161 offset:49216
	v_exp_f32_e32 v130, v130
	v_exp_f32_e32 v131, v131
	v_exp_f32_e32 v134, v134
	v_exp_f32_e32 v135, v135
	s_waitcnt lgkmcnt(4)
	v_mfma_scale_f32_32x32x64_f8f6f4 v[112:127], v[120:127], v[184:191], v[96:111], v234, v233 op_sel_hi:[0,0,0]
	v_exp_f32_e32 v136, v136
	v_exp_f32_e32 v137, v137
	v_exp_f32_e32 v140, v140
	v_exp_f32_e32 v141, v141
	s_waitcnt lgkmcnt(2)
	v_mfma_scale_f32_32x32x64_f8f6f4 v[112:127], v[194:201], v[176:183], v[112:127], v234, v233 op_sel_hi:[0,0,0]
	v_exp_f32_e32 v138, v138
	v_exp_f32_e32 v139, v139
	v_exp_f32_e32 v142, v142
	v_exp_f32_e32 v143, v143
	s_waitcnt lgkmcnt(0)
	v_mfma_scale_f32_32x32x64_f8f6f4 v[144:159], v[202:209], v[176:183], v[144:159], v234, v233 op_sel_hi:[0,0,0]
	ds_read_b128 v[194:197], v0 offset:55424
	ds_read_b128 v[198:201], v161 offset:55424
	ds_read_b128 v[202:205], v0 offset:49280
	ds_read_b128 v[206:209], v161 offset:49280
	v_exp_f32_e32 v0, v128
	v_exp_f32_e32 v161, v132
	v_cvt_pk_fp8_f32 v132, v0, v129
	v_cvt_pk_fp8_f32 v133, v161, v162
	v_cvt_pk_fp8_f32 v128, v14, v15
	v_cvt_pk_fp8_f32 v132, v130, v131 op_sel:[0,0,1]
	v_cvt_pk_fp8_f32 v133, v134, v135 op_sel:[0,0,1]
	s_waitcnt lgkmcnt(0)
	v_mfma_scale_f32_32x32x64_f8f6f4 v[112:127], v[194:201], v[168:175], v[112:127], v234, v233 op_sel_hi:[0,0,0]
	v_cvt_pk_fp8_f32 v129, v10, v11
	v_cvt_pk_fp8_f32 v130, v6, v7
	v_cvt_pk_fp8_f32 v134, v136, v137
	v_cvt_pk_fp8_f32 v131, v2, v3
	v_cvt_pk_fp8_f32 v135, v140, v141
	v_cvt_pk_fp8_f32 v128, v192, v193 op_sel:[0,0,1]
	v_cvt_pk_fp8_f32 v129, v12, v13 op_sel:[0,0,1]
	v_cvt_pk_fp8_f32 v130, v8, v9 op_sel:[0,0,1]
	v_cvt_pk_fp8_f32 v134, v138, v139 op_sel:[0,0,1]
	v_cvt_pk_fp8_f32 v131, v4, v5 op_sel:[0,0,1]
	v_cvt_pk_fp8_f32 v135, v142, v143 op_sel:[0,0,1]
	v_or_b32_e32 v10, s0, v218
	v_or_b32_e32 v11, s0, v250
	v_add_u32_e32 v10, v247, v10
	v_add_u32_e32 v11, v247, v11
	ds_read_b128 v[2:5], v10
	ds_read_b128 v[6:9], v11
	v_mfma_scale_f32_32x32x64_f8f6f4 v[144:159], v[202:209], v[168:175], v[144:159], v234, v233 op_sel_hi:[0,0,0]
	ds_read_b128 v[194:197], v10 offset:2048
	ds_read_b128 v[198:201], v11 offset:2048
	s_waitcnt lgkmcnt(2)
	v_mfma_scale_f32_32x32x64_f8f6f4 v[64:79], v[128:135], v[2:9], v[64:79], v234, v234 op_sel_hi:[0,0,0]
	ds_read_b128 v[2:5], v10 offset:4096
	ds_read_b128 v[6:9], v11 offset:4096
	v_mov_b32_e32 v161, v160
	v_mov_b32_e32 v162, v160
	v_mov_b32_e32 v163, v160
	v_mov_b32_e32 v164, v160
	v_mov_b32_e32 v165, v160
	v_mov_b32_e32 v166, v160
	v_mov_b32_e32 v167, v160
	s_waitcnt lgkmcnt(2)
	v_mfma_scale_f32_32x32x64_f8f6f4 v[48:63], v[128:135], v[194:201], v[48:63], v234, v234 op_sel_hi:[0,0,0]
	ds_read_b128 v[194:197], v10 offset:6144
	ds_read_b128 v[198:201], v11 offset:6144
	s_nop 2
	v_exp_f32_e32 v228, v144
	v_exp_f32_e32 v229, v145
	v_exp_f32_e32 v220, v146
	v_exp_f32_e32 v221, v147
	v_exp_f32_e32 v226, v148
	s_waitcnt lgkmcnt(2)
	v_mfma_scale_f32_32x32x64_f8f6f4 v[32:47], v[128:135], v[2:9], v[32:47], v234, v234 op_sel_hi:[0,0,0]
	v_exp_f32_e32 v227, v149
	v_exp_f32_e32 v224, v150
	v_exp_f32_e32 v225, v151
	v_exp_f32_e32 v222, v152
	v_exp_f32_e32 v223, v153
	v_max_f32_e32 v0, v144, v145
	v_max3_f32 v0, v0, v146, v147
	v_max3_f32 v0, v0, v148, v149
	v_max3_f32 v0, v0, v150, v151
	v_max3_f32 v0, v0, v152, v153
	s_waitcnt lgkmcnt(0)
	v_mfma_scale_f32_32x32x64_f8f6f4 v[16:31], v[128:135], v[194:201], v[16:31], v234, v234 op_sel_hi:[0,0,0]
	s_bitcmp0_b32 s15, 0
	s_cselect_b32 s1, 0x6000, 0
	v_add_u32_e32 v12, s1, v244
	v_add_u32_e32 v13, s1, v245
	v_add_u32_e32 v14, 0xf000, v12
	v_add_u32_e32 v15, 0xf000, v13
	ds_read_b128 v[202:205], v12 offset:61440
	ds_read_b128 v[206:209], v13 offset:61440
	ds_read_b128 v[194:197], v14 offset:6144
	ds_read_b128 v[198:201], v15 offset:6144
	v_max3_f32 v0, v0, v154, v155
	v_max3_f32 v0, v0, v156, v157
	v_max3_f32 v0, v0, v158, v159
	v_max3_f32 v0, v0, v112, v113
	v_max3_f32 v0, v0, v114, v115
	v_max3_f32 v0, v0, v116, v117
	v_max3_f32 v0, v0, v118, v119
	v_max3_f32 v0, v0, v120, v121
	v_max3_f32 v0, v0, v122, v123
	v_mfma_scale_f32_32x32x64_f8f6f4 v[80:95], v[128:135], v[160:167], v[80:95], v234, v234 op_sel_hi:[0,0,0]
	v_max3_f32 v0, v0, v124, v125
	v_max3_f32 v0, v0, v126, v127
	v_mov_b32_e32 v2, v0
	s_nop 1
	v_permlane32_swap_b32_e32 v0, v2
	v_max_f32_e32 v0, v0, v2
	v_cmp_ge_f32_e32 vcc, s67, v0
	v_exp_f32_e32 v162, v154
	s_cmp_lg_u64 vcc, exec
	v_exp_f32_e32 v163, v155
	v_exp_f32_e32 v166, v156
	v_exp_f32_e32 v167, v157
	v_exp_f32_e32 v164, v158
	v_exp_f32_e32 v165, v159
	s_cbranch_scc0 .LBB0_588
	v_add_f32_e32 v2, -4.0, v0
	v_max_f32_e32 v2, 0, v2
	v_exp_f32_e64 v0, -v2
	s_and_saveexec_b64 s[0:1], s[12:13]
	s_cbranch_execz .LBB0_587
	ds_write_b32 v243, v0 offset:128
	s_branch .LBB0_587
